# P4c plus attn0: Q-fragment vmcnt wait hoisted before the tile loop so the S phase no longer waits on the next-tile prefetch
# baseline (speedup 1.0000x reference)
; #define LAS __attribute__((address_space(3)))
; #define TIDX() tidx_from(wave_s_)
; template <int DQ, bool BIAS>
; __device__ __forceinline__ void attn_item_l0(const AttnItem& A, LAS unsigned char* lds, int wave_s_) {
;     ...
;     const int tid = TIDX(), lane = tid & 63, w = __builtin_amdgcn_readfirstlane(tid >> 6), r32 = lane & 31, hi = lane >> 5;
;     LAS float* lut = (LAS float*)(lds + OATT_LUT_OFF);
;     __syncthreads();
;     if (BIAS) { for (int i = tid; i < LUTN; i += NT) lut[i] = A.lut[i]; }
;     const int wlo = max(A.wlo0 + w * A.wstep_lo, A.t_lo), whi = min(A.whi0 + w * A.wstep, A.t_hi);
;     const int qrow = A.q_row0 + 64 * w;
;     bf16x8 qf[2][NKK];
; #pragma unroll
;     for (int qb = 0; qb < 2; ++qb)
; #pragma unroll
;         for (int kk = 0; kk < NKK; ++kk) qf[qb][kk] = *(const bf16x8*)(A.Q + (size_t)((wlo <= whi ? qrow : A.q_row0) + 32 * qb + r32) * A.q_stride + 16 * kk + 8 * hi);
;     if (DQ == 96) {
; #pragma unroll
;         for (int qb = 0; qb < 2; ++qb) {
;             const int row = (wlo <= whi ? qrow : A.q_row0) + 32 * qb + r32; const int pos = row < NPROMPT ? (row & (SEQ - 1)) : PAST + ((row - NPROMPT) & 31);
;             const float* rp = A.rope + (size_t)pos * 32 + 8 * hi;
;             const f32x4 c0 = *(const f32x4*)rp, c1 = *(const f32x4*)(rp + 4), s0 = *(const f32x4*)(rp + 16), s1 = *(const f32x4*)(rp + 20);
;             u32x4 w1, w2;
; #pragma unroll
;             for (int jp = 0; jp < 4; ++jp) {
;                 float o1[2], o2[2];
; #pragma unroll
;                 for (int e = 0; e < 2; ++e) { const int j = 2 * jp + e;
;                     const float x1 = __builtin_bit_cast(float, (unsigned)(unsigned short)qf[qb][NKK - 2][j] << 16), x2 = __builtin_bit_cast(float, (unsigned)(unsigned short)qf[qb][NKK - 1][j] << 16);
;                     const float c = j < 4 ? c0[j & 3] : c1[j & 3], s = j < 4 ? s0[j & 3] : s1[j & 3];
;                     o1[e] = x1 * c - x2 * s; o2[e] = x1 * s + x2 * c; }
;                 w1[jp] = pk2(o1[0], o1[1]); w2[jp] = pk2(o2[0], o2[1]);
;             }
;             qf[qb][NKK - 2] = __builtin_bit_cast(bf16x8, w1); qf[qb][NKK - 1] = __builtin_bit_cast(bf16x8, w2);
;         }
;     }
;     f32x16 o[2][2];
; #pragma unroll
;     for (int d = 0; d < 2; ++d)
; #pragma unroll
;         for (int qb = 0; qb < 2; ++qb)
; #pragma unroll
;             for (int i = 0; i < 16; ++i) o[d][qb][i] = 0.f;
.LBB0_1033:
	s_or_b64 exec, exec, s[10:11]
	s_ashr_i32 s6, s24, 6
	s_mul_i32 s7, s6, s21
	s_mul_i32 s6, s6, s20
	s_add_i32 s6, s6, s22
	s_add_i32 s7, s7, s23
	s_min_i32 s71, s6, s90
	s_and_b32 s6, s24, 0xffffffc0
	s_max_i32 s70, s7, s91
	s_add_i32 s89, s6, s19
	s_cmp_le_i32 s70, s71
	s_cselect_b64 s[92:93], -1, 0
	s_cmp_gt_i32 s70, s71
	v_and_b32_e32 v245, 31, v4
	s_cselect_b32 s7, s19, s89
	v_add_u32_e32 v6, s7, v245
	v_ashrrev_i32_e32 v0, 3, v0
	s_lshl_b32 s7, s91, 6
	v_bfe_u32 v5, v4, 5, 1
	s_add_i32 s72, s18, s7
	v_ashrrev_i32_e32 v1, 31, v0
	v_lshlrev_b32_e32 v2, 4, v5
	v_mov_b32_e32 v3, v197
	v_ashrrev_i32_e32 v7, 31, v6
	v_lshl_add_u64 v[12:13], v[0:1], 0, s[72:73]
	v_lshl_add_u64 v[8:9], s[8:9], 0, v[2:3]
	v_lshlrev_b64 v[10:11], 11, v[6:7]
	v_mul_lo_u32 v7, v13, s4
	v_mul_lo_u32 v14, v12, s5
	v_mad_u64_u32 v[12:13], s[8:9], v12, s4, 0
	v_add3_u32 v13, v13, v14, v7
	v_add_u32_e32 v6, 32, v6
	v_and_b32_e32 v3, 7, v4
	v_lshlrev_b64 v[12:13], 1, v[12:13]
	v_ashrrev_i32_e32 v7, 31, v6
	v_lshl_add_u64 v[14:15], s[74:75], 0, v[12:13]
	v_lshlrev_b32_e32 v196, 4, v3
	v_lshl_add_u64 v[12:13], s[82:83], 0, v[12:13]
	v_lshlrev_b64 v[6:7], 11, v[6:7]
	v_lshl_add_u64 v[14:15], v[14:15], 0, v[196:197]
	v_lshl_add_u64 v[12:13], v[12:13], 0, v[196:197]
	v_lshl_add_u64 v[6:7], v[8:9], 0, v[6:7]
	v_lshl_add_u64 v[10:11], v[8:9], 0, v[10:11]
	global_load_dwordx4 v[128:131], v[14:15], off
	global_load_dwordx4 v[148:151], v[12:13], off
	global_load_dwordx4 v[132:135], v[10:11], off
	global_load_dwordx4 v[136:139], v[10:11], off offset:32
	global_load_dwordx4 v[140:143], v[10:11], off offset:64
	global_load_dwordx4 v[144:147], v[10:11], off offset:96
	global_load_dwordx4 v[152:155], v[6:7], off
	global_load_dwordx4 v[156:159], v[6:7], off offset:32
	global_load_dwordx4 v[160:163], v[6:7], off offset:64
	global_load_dwordx4 v[164:167], v[6:7], off offset:96
	v_and_b32_e32 v4, 63, v4
	v_mov_b32_e32 v6, s16
	v_lshlrev_b32_e32 v170, 3, v5
	v_cmp_gt_u32_e32 vcc, 32, v4
	v_lshlrev_b32_e32 v246, 2, v5
	v_lshlrev_b32_e32 v5, 2, v4
	v_add_u32_e32 v4, 0, v196
	s_movk_i32 s8, 0xd0
	v_cndmask_b32_e32 v168, 0, v6, vcc
	v_mul_u32_u24_e32 v3, 0x430, v3
	v_lshlrev_b32_e32 v6, 1, v0
	v_mad_u64_u32 v[172:173], s[8:9], v0, s8, v[4:5]
	v_mov_b32_e32 v47, 0
	v_add3_u32 v171, v4, v3, v6
	s_cmp_le_u32 s91, s90
	v_xor_b32_e32 v173, 0x80, v5
	s_waitcnt vmcnt(9)
	ds_write_b128 v172, v[128:131]
	s_waitcnt vmcnt(8)
	ds_write_b16 v171, v148 offset:26624
	ds_write_b16_d16_hi v171, v148 offset:26760
	ds_write_b16 v171, v149 offset:26896
	ds_write_b16_d16_hi v171, v149 offset:27032
	ds_write_b16 v171, v150 offset:27168
	ds_write_b16_d16_hi v171, v150 offset:27304
	ds_write_b16 v171, v151 offset:27440
	ds_write_b16_d16_hi v171, v151 offset:27576
	s_waitcnt lgkmcnt(0)
	s_barrier
	s_cbranch_scc0 .LBB0_1042
	s_add_i32 s17, s17, s6
	v_add_u32_e32 v247, 0, v2
	v_lshl_or_b32 v2, s91, 8, v2
	v_add_lshl_u32 v3, s17, v245, 2
	s_add_i32 s72, s72, 64
	v_sub_u32_e32 v2, v2, v3
	v_readlane_b32 s6, v255, 3
	s_lshl_b32 s8, s4, 1
	v_lshl_add_u64 v[0:1], v[0:1], 0, s[72:73]
	v_add_u32_e32 v251, s6, v2
	v_add3_u32 v252, s7, 59, v246
	v_mad_u64_u32 v[174:175], s[6:7], s8, v0, v[196:197]
	s_lshr_b64 s[6:7], s[4:5], 31
	v_mul_lo_u32 v1, s8, v1
	v_mul_lo_u32 v0, s6, v0
	v_add3_u32 v175, v0, v175, v1
	v_mov_b32_e32 v0, 0
	v_sub_u32_e32 v248, v247, v170
	v_mul_u32_u24_e32 v249, 0xd0, v245
	v_mul_u32_u24_e32 v250, 0x88, v245
	s_lshl_b64 s[94:95], s[4:5], 7
	s_mov_b32 s72, 0
	v_mov_b32_e32 v178, v179
	v_mov_b32_e32 v1, v0
	v_mov_b32_e32 v2, v0
	v_mov_b32_e32 v3, v0
	v_mov_b32_e32 v4, v0
	v_mov_b32_e32 v5, v0
	v_mov_b32_e32 v6, v0
	v_mov_b32_e32 v7, v0
	v_mov_b32_e32 v8, v0
	v_mov_b32_e32 v9, v0
	v_mov_b32_e32 v10, v0
	v_mov_b32_e32 v11, v0
	v_mov_b32_e32 v12, v0
	v_mov_b32_e32 v13, v0
	v_mov_b32_e32 v14, v0
	v_mov_b32_e32 v15, v0
	v_mov_b32_e32 v48, v0
	v_mov_b32_e32 v49, v0
	v_mov_b32_e32 v50, v0
	v_mov_b32_e32 v51, v0
	v_mov_b32_e32 v52, v0
	v_mov_b32_e32 v53, v0
	v_mov_b32_e32 v54, v0
	v_mov_b32_e32 v55, v0
	v_mov_b32_e32 v56, v0
	v_mov_b32_e32 v57, v0
	v_mov_b32_e32 v58, v0
	v_mov_b32_e32 v59, v0
	v_mov_b32_e32 v60, v0
	v_mov_b32_e32 v61, v0
	v_mov_b32_e32 v62, v0
	v_mov_b32_e32 v63, v0
	v_mov_b32_e32 v16, v0
	v_mov_b32_e32 v17, v0
	v_mov_b32_e32 v18, v0
	v_mov_b32_e32 v19, v0
	v_mov_b32_e32 v20, v0
	v_mov_b32_e32 v21, v0
	v_mov_b32_e32 v22, v0
	v_mov_b32_e32 v23, v0
	v_mov_b32_e32 v24, v0
	v_mov_b32_e32 v25, v0
	v_mov_b32_e32 v26, v0
	v_mov_b32_e32 v27, v0
	v_mov_b32_e32 v28, v0
	v_mov_b32_e32 v29, v0
	v_mov_b32_e32 v30, v0
	v_mov_b32_e32 v31, v0
	v_mov_b32_e32 v32, v0
	v_mov_b32_e32 v33, v0
	v_mov_b32_e32 v34, v0
	v_mov_b32_e32 v35, v0
	v_mov_b32_e32 v36, v0
	v_mov_b32_e32 v37, v0
	v_mov_b32_e32 v38, v0
	v_mov_b32_e32 v39, v0
	v_mov_b32_e32 v40, v0
	v_mov_b32_e32 v41, v0
	v_mov_b32_e32 v42, v0
	v_mov_b32_e32 v43, v0
	v_mov_b32_e32 v44, v0
	v_mov_b32_e32 v45, v0
	v_mov_b32_e32 v46, v0
	v_mov_b32_e32 v47, v0
	v_mov_b32_e32 v169, v168
	s_waitcnt vmcnt(0)
	s_branch .LBB0_1036

; #define LAS __attribute__((address_space(3)))
; __device__ __forceinline__ int crow(int i, int hi) { return (i & 3) + 8 * (i >> 2) + 4 * hi; }
; #define MFMA32(a, b, c) __builtin_amdgcn_mfma_f32_32x32x16_bf16((a), (b), (c), 0, 0, 0)
; template <int DQ, bool BIAS>
; __device__ __forceinline__ void attn_item_l0(const AttnItem& A, LAS unsigned char* lds, int wave_s_) {
;     ...
;         if (t >= wlo && t <= whi) {
;             LAS unsigned char* kb = lds + buf * OKBUF; LAS unsigned char* vb = lds + 2 * OKBUF + buf * OVBUF;
;             f32x16 s[2][2];
; #pragma unroll
;             for (int kbk = 0; kbk < 2; ++kbk) {
; #pragma unroll
;                 for (int qb = 0; qb < 2; ++qb)
; #pragma unroll
;                     for (int i = 0; i < 16; ++i) s[kbk][qb][i] = 0.f;
; #pragma unroll
;                 for (int kk = 0; kk < NKK; ++kk) {
;                     const bf16x8 kf = *(const LAS bf16x8*)(kb + ((32 * kbk + r32) * OKSTR + 16 * kk + 8 * hi) * 2);
;                     s[kbk][0] = MFMA32(kf, qf[0][kk], s[kbk][0]);
;                     s[kbk][1] = MFMA32(kf, qf[1][kk], s[kbk][1]);
;                 }
;             }
; #pragma unroll
;             for (int qb = 0; qb < 2; ++qb) {
;                 const int qk = A.q_kidx0 + 64 * w + 32 * qb + r32;
;                 float mx = -3.0e38f;
; #pragma unroll
;                 for (int kbk = 0; kbk < 2; ++kbk)
; #pragma unroll
;                     for (int i = 0; i < 16; ++i) {
;                         const int kidx = 64 * t + 32 * kbk + crow(i, hi);
;                         float v = s[kbk][qb][i] * A.scale2;
;                         if (BIAS) v += lut[kidx - qk + LUT0];
;                         if (kidx >= A.nkeys) v = -1.0e30f;
;                         s[kbk][qb][i] = v; mx = fmaxf(mx, v);
.LBB0_1038:
	s_cmp_lt_u32 s91, s70
	s_cselect_b64 s[4:5], -1, 0
	s_cmp_gt_i32 s91, s71
	s_cselect_b64 s[6:7], -1, 0
	s_or_b64 s[4:5], s[4:5], s[6:7]
	s_and_b64 vcc, exec, s[4:5]
	s_cbranch_vccnz .LBB0_1040
	s_mul_i32 s4, s72, 0x3400
	v_add3_u32 v176, v247, s4, v249
	ds_read_b128 v[64:67], v176
	ds_read_b128 v[68:71], v176 offset:32
	s_mov_b32 s3, 0xff61b1e6
	v_subrev_u32_e32 v187, 49, v252
	v_cmp_gt_u32_e64 s[14:15], s2, v187
	s_waitcnt lgkmcnt(1)
	v_mfma_f32_32x32x16_bf16 v[112:127], v[64:67], v[132:135], 0
	ds_read_b128 v[180:183], v176 offset:6688
	v_subrev_u32_e32 v187, 48, v252
	v_cmp_gt_u32_e64 s[18:19], s2, v187
	v_subrev_u32_e32 v187, 43, v252
	v_cmp_gt_u32_e64 s[16:17], s2, v187
	v_subrev_u32_e32 v187, 42, v252
	v_cmp_gt_u32_e64 s[20:21], s2, v187
	s_nop 0
	v_mfma_f32_32x32x16_bf16 v[80:95], v[64:67], v[152:155], 0
	ds_read_b128 v[64:67], v176 offset:64
	v_subrev_u32_e32 v187, 41, v252
	v_cmp_gt_u32_e64 s[22:23], s2, v187
	v_subrev_u32_e32 v187, 40, v252
	v_cmp_gt_u32_e64 s[24:25], s2, v187
	v_subrev_u32_e32 v187, 35, v252
	v_cmp_gt_u32_e64 s[26:27], s2, v187
	s_waitcnt lgkmcnt(2)
	v_mfma_f32_32x32x16_bf16 v[112:127], v[68:71], v[136:139], v[112:127]
	v_subrev_u32_e32 v187, 34, v252
	v_cmp_gt_u32_e64 s[28:29], s2, v187
	v_subrev_u32_e32 v187, 33, v252
	v_cmp_gt_u32_e64 s[30:31], s2, v187
	v_subrev_u32_e32 v187, 32, v252
	v_cmp_gt_u32_e64 s[34:35], s2, v187
	v_subrev_u32_e32 v189, 27, v252
	s_nop 0
	v_mfma_f32_32x32x16_bf16 v[80:95], v[68:71], v[156:159], v[80:95]
	v_cmp_gt_u32_e64 s[36:37], s2, v189
	v_subrev_u32_e32 v189, 25, v252
	v_cmp_gt_u32_e64 s[40:41], s2, v189
	v_cmp_gt_u32_e64 s[66:67], s2, v252
	ds_read2_b32 v[210:211], v251 offset0:48 offset1:49
	ds_read2_b32 v[238:239], v251 offset1:1
	ds_read2_b32 v[212:213], v251 offset0:50 offset1:51
	s_waitcnt lgkmcnt(3)
	v_mfma_f32_32x32x16_bf16 v[112:127], v[64:67], v[140:143], v[112:127]
	ds_read2_b32 v[214:215], v251 offset0:56 offset1:57
	ds_read2_b32 v[216:217], v251 offset0:58 offset1:59
	s_nop 0
	v_mfma_f32_32x32x16_bf16 v[80:95], v[64:67], v[160:163], v[80:95]
	ds_read_b128 v[64:67], v176 offset:96
	s_waitcnt lgkmcnt(0)
	v_mfma_f32_32x32x16_bf16 v[112:127], v[64:67], v[144:147], v[112:127]
	s_nop 0
	v_mfma_f32_32x32x16_bf16 v[80:95], v[64:67], v[164:167], v[80:95]
	ds_read_b128 v[64:67], v176 offset:6656
	s_nop 8
	v_fmamk_f32 v120, v120, 0x3e38aa3b, v210
	v_fmamk_f32 v121, v121, 0x3e38aa3b, v211
	v_cndmask_b32_e64 v120, v243, v120, s[16:17]
	v_cndmask_b32_e64 v121, v243, v121, s[20:21]
	v_fmamk_f32 v122, v122, 0x3e38aa3b, v212
	v_fmamk_f32 v123, v123, 0x3e38aa3b, v213
	s_waitcnt lgkmcnt(0)
	v_mfma_f32_32x32x16_bf16 v[96:111], v[64:67], v[132:135], 0
	v_cndmask_b32_e64 v122, v243, v122, s[22:23]
	v_cndmask_b32_e64 v123, v243, v123, s[24:25]
	v_fmamk_f32 v124, v124, 0x3e38aa3b, v214
	v_fmamk_f32 v125, v125, 0x3e38aa3b, v215
	v_cndmask_b32_e64 v124, v243, v124, s[26:27]
	v_cndmask_b32_e64 v125, v243, v125, s[28:29]
	v_fmamk_f32 v80, v80, 0x3e38aa3b, v238
	v_mfma_f32_32x32x16_bf16 v[64:79], v[64:67], v[152:155], 0
	v_fmac_f32_e32 v239, 0x3e38aa3b, v81
	v_fmamk_f32 v126, v126, 0x3e38aa3b, v216
	v_fmamk_f32 v127, v127, 0x3e38aa3b, v217
	v_cndmask_b32_e64 v126, v243, v126, s[30:31]
	v_cndmask_b32_e64 v127, v243, v127, s[34:35]
	v_mfma_f32_32x32x16_bf16 v[96:111], v[180:183], v[136:139], v[96:111]
	v_mfma_f32_32x32x16_bf16 v[64:79], v[180:183], v[156:159], v[64:79]
	ds_read_b128 v[180:183], v176 offset:6720
	s_waitcnt lgkmcnt(0)
	v_mfma_f32_32x32x16_bf16 v[96:111], v[180:183], v[140:143], v[96:111]
	v_mfma_f32_32x32x16_bf16 v[64:79], v[180:183], v[160:163], v[64:79]
	ds_read_b128 v[180:183], v176 offset:6752
	ds_read2_b32 v[176:177], v251 offset0:32 offset1:33
	s_waitcnt lgkmcnt(0)
	v_fmamk_f32 v112, v112, 0x3e38aa3b, v176
	v_mfma_f32_32x32x16_bf16 v[96:111], v[180:183], v[144:147], v[96:111]
	v_fmamk_f32 v113, v113, 0x3e38aa3b, v177
	v_mfma_f32_32x32x16_bf16 v[64:79], v[180:183], v[164:167], v[64:79]
	v_subrev_u32_e32 v180, 59, v252
	v_cmp_gt_u32_e32 vcc, s2, v180
	v_subrev_u32_e32 v183, 57, v252
	v_cmp_gt_u32_e64 s[4:5], s2, v183
	v_cndmask_b32_e32 v180, v243, v112, vcc
	v_subrev_u32_e32 v112, 58, v252
	v_cmp_gt_u32_e64 s[6:7], s2, v112
	v_subrev_u32_e32 v183, 51, v252
	v_cmp_gt_u32_e64 s[8:9], s2, v183
	v_cndmask_b32_e64 v181, v243, v113, s[6:7]
	ds_read2_b32 v[112:113], v251 offset0:34 offset1:35
	v_subrev_u32_e32 v183, 50, v252
	v_max3_f32 v182, v180, s3, v181
	v_cmp_gt_u32_e64 s[12:13], s2, v183
	v_fmamk_f32 v64, v64, 0x3e38aa3b, v176
	s_waitcnt lgkmcnt(0)
	v_fmamk_f32 v114, v114, 0x3e38aa3b, v112
	v_cndmask_b32_e64 v184, v243, v114, s[4:5]
	v_subrev_u32_e32 v114, 56, v252
	v_fmamk_f32 v115, v115, 0x3e38aa3b, v113
	v_cmp_gt_u32_e64 s[10:11], s2, v114
	v_fmac_f32_e32 v177, 0x3e38aa3b, v65
	v_fmamk_f32 v65, v66, 0x3e38aa3b, v112
	v_cndmask_b32_e64 v185, v243, v115, s[10:11]
	ds_read2_b32 v[114:115], v251 offset0:40 offset1:41
	v_max3_f32 v182, v182, v184, v185
	v_fmac_f32_e32 v113, 0x3e38aa3b, v67
	v_fmac_f32_e32 v211, 0x3e38aa3b, v73
	v_fmac_f32_e32 v213, 0x3e38aa3b, v75
	s_waitcnt lgkmcnt(0)
	v_fmamk_f32 v116, v116, 0x3e38aa3b, v114
	v_fmamk_f32 v117, v117, 0x3e38aa3b, v115
	v_cndmask_b32_e64 v116, v243, v116, s[8:9]
	v_cndmask_b32_e64 v117, v243, v117, s[12:13]
	v_max3_f32 v186, v182, v116, v117
	ds_read2_b32 v[182:183], v251 offset0:42 offset1:43
	v_fmac_f32_e32 v115, 0x3e38aa3b, v69
	v_fmac_f32_e32 v215, 0x3e38aa3b, v77
	v_fmac_f32_e32 v217, 0x3e38aa3b, v79
	v_cndmask_b32_e64 v79, v243, v217, s[66:67]
	s_waitcnt lgkmcnt(0)
; __device__ __forceinline__ float shx(float v, int lane, int o) { return __builtin_bit_cast(float, __builtin_amdgcn_ds_bpermute((lane ^ o) << 2, __builtin_bit_cast(int, v))); }
; __device__ __forceinline__ int crow(int i, int hi) { return (i & 3) + 8 * (i >> 2) + 4 * hi; }
; template <int DQ, bool BIAS>
; __device__ __forceinline__ void attn_item_l0(const AttnItem& A, LAS unsigned char* lds, int wave_s_) {
;     ...
; #pragma unroll
;             for (int qb = 0; qb < 2; ++qb) {
;                 const int qk = A.q_kidx0 + 64 * w + 32 * qb + r32;
;                 float mx = -3.0e38f;
; #pragma unroll
;                 for (int kbk = 0; kbk < 2; ++kbk)
; #pragma unroll
;                     for (int i = 0; i < 16; ++i) {
;                         const int kidx = 64 * t + 32 * kbk + crow(i, hi);
;                         float v = s[kbk][qb][i] * A.scale2;
;                         if (BIAS) v += lut[kidx - qk + LUT0];
;                         if (kidx >= A.nkeys) v = -1.0e30f;
;                         s[kbk][qb][i] = v; mx = fmaxf(mx, v);
;                     }
;                 mx = fmaxf(mx, shx(mx, lane, 32));
;                 const float mnew = fmaxf(mrun[qb], mx), alpha = __builtin_amdgcn_exp2f(mrun[qb] - mnew);
;                 mrun[qb] = mnew;
;                 float ls = 0.f;
; #pragma unroll
;                 for (int kbk = 0; kbk < 2; ++kbk)
; #pragma unroll
;                     for (int i = 0; i < 16; ++i) { const float p = __builtin_amdgcn_exp2f(s[kbk][qb][i] - mnew); s[kbk][qb][i] = p; ls += p; }
;                 lrun[qb] = lrun[qb] * alpha + ls;
; #pragma unroll
;                 for (int d = 0; d < 2; ++d)
; #pragma unroll
;                     for (int i = 0; i < 16; ++i) o[d][qb][i] *= alpha;
;             }
	v_fmamk_f32 v118, v118, 0x3e38aa3b, v182
	v_fmamk_f32 v119, v119, 0x3e38aa3b, v183
	v_cndmask_b32_e64 v118, v243, v118, s[14:15]
	v_cndmask_b32_e64 v119, v243, v119, s[18:19]
	v_max3_f32 v186, v186, v118, v119
	v_max3_f32 v186, v186, v120, v121
	v_max3_f32 v186, v186, v122, v123
	v_max3_f32 v186, v186, v124, v125
	v_max3_f32 v188, v186, v126, v127
	ds_read2_b32 v[186:187], v251 offset0:64 offset1:65
	v_fmac_f32_e32 v183, 0x3e38aa3b, v71
	s_waitcnt lgkmcnt(0)
	v_fmamk_f32 v96, v96, 0x3e38aa3b, v186
	v_subrev_u32_e32 v186, 26, v252
	v_fmac_f32_e32 v187, 0x3e38aa3b, v97
	v_cmp_gt_u32_e64 s[38:39], s2, v186
	v_cndmask_b32_e64 v96, v243, v96, s[36:37]
	s_nop 0
	v_cndmask_b32_e64 v97, v243, v187, s[38:39]
	ds_read2_b32 v[186:187], v251 offset0:66 offset1:67
	v_max3_f32 v188, v188, v96, v97
	s_waitcnt lgkmcnt(0)
	v_fmamk_f32 v98, v98, 0x3e38aa3b, v186
	v_cndmask_b32_e64 v189, v243, v98, s[40:41]
	v_subrev_u32_e32 v98, 24, v252
	v_fmac_f32_e32 v187, 0x3e38aa3b, v99
	v_cmp_gt_u32_e64 s[42:43], s2, v98
	ds_read2_b32 v[98:99], v251 offset0:72 offset1:73
	s_waitcnt lgkmcnt(0)
	v_fmamk_f32 v98, v100, 0x3e38aa3b, v98
	v_cndmask_b32_e64 v187, v243, v187, s[42:43]
	v_max3_f32 v186, v188, v189, v187
	v_subrev_u32_e32 v188, 19, v252
	v_cmp_gt_u32_e64 s[44:45], s2, v188
	v_fmac_f32_e32 v99, 0x3e38aa3b, v101
	v_subrev_u32_e32 v188, 17, v252
	v_cndmask_b32_e64 v100, v243, v98, s[44:45]
	v_subrev_u32_e32 v98, 18, v252
	v_cmp_gt_u32_e64 s[46:47], s2, v98
	v_cmp_gt_u32_e64 s[48:49], s2, v188
	v_add_u32_e32 v188, -11, v252
	v_cndmask_b32_e64 v101, v243, v99, s[46:47]
	ds_read2_b32 v[98:99], v251 offset0:74 offset1:75
	v_cmp_gt_u32_e64 s[52:53], s2, v188
	v_add_u32_e32 v188, -9, v252
	v_cmp_gt_u32_e64 s[56:57], s2, v188
	v_add_u32_e32 v188, -3, v252
	s_waitcnt lgkmcnt(0)
	v_fmamk_f32 v98, v102, 0x3e38aa3b, v98
	v_cndmask_b32_e64 v102, v243, v98, s[48:49]
	v_add_u32_e32 v98, -16, v252
	v_fmac_f32_e32 v99, 0x3e38aa3b, v103
	v_cmp_gt_u32_e64 s[50:51], s2, v98
	v_cmp_gt_u32_e64 s[60:61], s2, v188
	v_max3_f32 v186, v186, v100, v101
	v_cndmask_b32_e64 v103, v243, v99, s[50:51]
	ds_read2_b32 v[98:99], v251 offset0:80 offset1:81
	v_max3_f32 v186, v186, v102, v103
	v_add_u32_e32 v188, -1, v252
	v_cmp_gt_u32_e64 s[64:65], s2, v188
	v_cndmask_b32_e64 v67, v243, v113, s[42:43]
	s_waitcnt lgkmcnt(0)
	v_fmamk_f32 v98, v104, 0x3e38aa3b, v98
	v_cndmask_b32_e64 v104, v243, v98, s[52:53]
	v_add_u32_e32 v98, -10, v252
	v_fmac_f32_e32 v99, 0x3e38aa3b, v105
	v_cmp_gt_u32_e64 s[54:55], s2, v98
	v_cndmask_b32_e64 v69, v243, v115, s[46:47]
	v_cndmask_b32_e64 v71, v243, v183, s[50:51]
	v_cndmask_b32_e64 v105, v243, v99, s[54:55]
	ds_read2_b32 v[98:99], v251 offset0:82 offset1:83
	v_max3_f32 v186, v186, v104, v105
	v_cndmask_b32_e64 v73, v243, v211, s[54:55]
	s_waitcnt lgkmcnt(0)
	v_fmamk_f32 v98, v106, 0x3e38aa3b, v98
	v_cndmask_b32_e64 v106, v243, v98, s[56:57]
	v_add_u32_e32 v98, -8, v252
	v_fmac_f32_e32 v99, 0x3e38aa3b, v107
	v_cmp_gt_u32_e64 s[58:59], s2, v98
	s_nop 1
	v_cndmask_b32_e64 v107, v243, v99, s[58:59]
	ds_read2_b32 v[98:99], v251 offset0:88 offset1:89
	v_max3_f32 v186, v186, v106, v107
	v_cndmask_b32_e64 v75, v243, v213, s[58:59]
	s_waitcnt lgkmcnt(0)
	v_fmamk_f32 v98, v108, 0x3e38aa3b, v98
	v_cndmask_b32_e64 v108, v243, v98, s[60:61]
	v_add_u32_e32 v98, -2, v252
	v_fmac_f32_e32 v99, 0x3e38aa3b, v109
	v_cmp_gt_u32_e64 s[62:63], s2, v98
	s_nop 1
	v_cndmask_b32_e64 v109, v243, v99, s[62:63]
	ds_read2_b32 v[98:99], v251 offset0:90 offset1:91
	v_max3_f32 v186, v186, v108, v109
	v_cndmask_b32_e64 v77, v243, v215, s[62:63]
	s_waitcnt lgkmcnt(0)
	v_fmamk_f32 v98, v110, 0x3e38aa3b, v98
	v_fmac_f32_e32 v99, 0x3e38aa3b, v111
	v_cndmask_b32_e64 v110, v243, v98, s[64:65]
	v_cndmask_b32_e64 v99, v243, v99, s[66:67]
	v_max3_f32 v98, v186, v110, v99
	ds_bpermute_b32 v111, v173, v98
	s_movk_i32 s67, 0x1fff
	s_waitcnt lgkmcnt(0)
	v_max3_f32 v196, v178, v98, v111
	v_sub_f32_e32 v98, v180, v196
	v_exp_f32_e32 v218, v98
	v_sub_f32_e32 v98, v181, v196
	v_exp_f32_e32 v220, v98
	v_sub_f32_e32 v98, v184, v196
	v_exp_f32_e32 v222, v98
	v_sub_f32_e32 v98, v185, v196
	v_exp_f32_e32 v224, v98
	v_sub_f32_e32 v98, v116, v196
	v_exp_f32_e32 v226, v98
	v_sub_f32_e32 v98, v117, v196
	v_exp_f32_e32 v228, v98
	v_sub_f32_e32 v98, v118, v196
	v_exp_f32_e32 v230, v98
	v_sub_f32_e32 v98, v119, v196
	v_exp_f32_e32 v232, v98
	v_sub_f32_e32 v98, v120, v196
	v_exp_f32_e32 v184, v98
	v_sub_f32_e32 v98, v121, v196
	v_exp_f32_e32 v186, v98
	v_sub_f32_e32 v98, v122, v196
	v_exp_f32_e32 v188, v98
	v_sub_f32_e32 v98, v123, v196
	v_sub_f32_e32 v96, v96, v196
	v_exp_f32_e32 v190, v98
	v_sub_f32_e32 v98, v124, v196
	v_exp_f32_e32 v116, v96
	v_sub_f32_e32 v96, v97, v196
	v_exp_f32_e32 v192, v98
	v_sub_f32_e32 v98, v125, v196
	v_exp_f32_e32 v118, v96
	v_sub_f32_e32 v96, v189, v196
	v_exp_f32_e32 v194, v98
	v_sub_f32_e32 v98, v126, v196
	v_exp_f32_e32 v120, v96
	v_sub_f32_e32 v96, v187, v196
	v_exp_f32_e32 v206, v98
	v_sub_f32_e32 v98, v127, v196
	v_exp_f32_e32 v122, v96
	v_sub_f32_e32 v96, v100, v196
	v_sub_f32_e32 v97, v105, v196
	v_exp_f32_e32 v208, v98
	v_exp_f32_e32 v124, v96
	v_sub_f32_e32 v96, v101, v196
	v_exp_f32_e32 v98, v97
	v_sub_f32_e32 v97, v106, v196
	v_exp_f32_e32 v126, v96
	v_sub_f32_e32 v96, v102, v196
	v_exp_f32_e32 v100, v97
	v_sub_f32_e32 v97, v107, v196
	v_sub_f32_e32 v111, v178, v196
	v_exp_f32_e32 v178, v96
	v_sub_f32_e32 v96, v103, v196
	v_exp_f32_e32 v102, v97
	v_sub_f32_e32 v97, v108, v196
	v_exp_f32_e32 v180, v96
	v_sub_f32_e32 v96, v104, v196
	v_exp_f32_e32 v104, v97
	v_sub_f32_e32 v97, v109, v196
	v_exp_f32_e32 v106, v97
	v_sub_f32_e32 v97, v110, v196
	v_exp_f32_e32 v108, v97
	v_sub_f32_e32 v97, v99, v196
	v_exp_f32_e32 v110, v97
	v_cndmask_b32_e32 v97, v243, v80, vcc
	ds_read2_b32 v[80:81], v251 offset0:2 offset1:3
	v_cndmask_b32_e64 v99, v243, v239, s[6:7]
	v_max3_f32 v101, v97, s3, v99
	v_exp_f32_e32 v96, v96
	v_exp_f32_e32 v234, v111
	s_waitcnt lgkmcnt(0)
; __device__ __forceinline__ float shx(float v, int lane, int o) { return __builtin_bit_cast(float, __builtin_amdgcn_ds_bpermute((lane ^ o) << 2, __builtin_bit_cast(int, v))); }
; __device__ __forceinline__ int crow(int i, int hi) { return (i & 3) + 8 * (i >> 2) + 4 * hi; }
; template <int DQ, bool BIAS>
; __device__ __forceinline__ void attn_item_l0(const AttnItem& A, LAS unsigned char* lds, int wave_s_) {
;     ...
; #pragma unroll
;             for (int qb = 0; qb < 2; ++qb) {
;                 const int qk = A.q_kidx0 + 64 * w + 32 * qb + r32;
;                 float mx = -3.0e38f;
; #pragma unroll
;                 for (int kbk = 0; kbk < 2; ++kbk)
; #pragma unroll
;                     for (int i = 0; i < 16; ++i) {
;                         const int kidx = 64 * t + 32 * kbk + crow(i, hi);
;                         float v = s[kbk][qb][i] * A.scale2;
;                         if (BIAS) v += lut[kidx - qk + LUT0];
;                         if (kidx >= A.nkeys) v = -1.0e30f;
;                         s[kbk][qb][i] = v; mx = fmaxf(mx, v);
;                     }
;                 mx = fmaxf(mx, shx(mx, lane, 32));
;                 const float mnew = fmaxf(mrun[qb], mx), alpha = __builtin_amdgcn_exp2f(mrun[qb] - mnew);
;                 mrun[qb] = mnew;
;                 float ls = 0.f;
; #pragma unroll
;                 for (int kbk = 0; kbk < 2; ++kbk)
; #pragma unroll
;                     for (int i = 0; i < 16; ++i) { const float p = __builtin_amdgcn_exp2f(s[kbk][qb][i] - mnew); s[kbk][qb][i] = p; ls += p; }
;                 lrun[qb] = lrun[qb] * alpha + ls;
; #pragma unroll
;                 for (int d = 0; d < 2; ++d)
; #pragma unroll
;                     for (int i = 0; i < 16; ++i) o[d][qb][i] *= alpha;
;             }
	v_fmamk_f32 v80, v82, 0x3e38aa3b, v80
	v_fmac_f32_e32 v81, 0x3e38aa3b, v83
	v_cndmask_b32_e64 v82, v243, v80, s[4:5]
	v_cndmask_b32_e64 v83, v243, v81, s[10:11]
	ds_read2_b32 v[80:81], v251 offset0:8 offset1:9
	v_max3_f32 v101, v101, v82, v83
	v_pk_mul_f32 v[46:47], v[46:47], v[234:235] op_sel_hi:[1,0]
	v_pk_mul_f32 v[44:45], v[44:45], v[234:235] op_sel_hi:[1,0]
	v_pk_mul_f32 v[42:43], v[42:43], v[234:235] op_sel_hi:[1,0]
	s_waitcnt lgkmcnt(0)
	v_fmamk_f32 v80, v84, 0x3e38aa3b, v80
	v_fmac_f32_e32 v81, 0x3e38aa3b, v85
	v_cndmask_b32_e64 v84, v243, v80, s[8:9]
	v_cndmask_b32_e64 v85, v243, v81, s[12:13]
	ds_read2_b32 v[80:81], v251 offset0:10 offset1:11
	v_max3_f32 v101, v101, v84, v85
	v_pk_mul_f32 v[40:41], v[40:41], v[234:235] op_sel_hi:[1,0]
	v_pk_mul_f32 v[38:39], v[38:39], v[234:235] op_sel_hi:[1,0]
	v_pk_mul_f32 v[36:37], v[36:37], v[234:235] op_sel_hi:[1,0]
	s_waitcnt lgkmcnt(0)
	v_fmamk_f32 v80, v86, 0x3e38aa3b, v80
	v_fmac_f32_e32 v81, 0x3e38aa3b, v87
	v_cndmask_b32_e64 v86, v243, v80, s[14:15]
	v_cndmask_b32_e64 v87, v243, v81, s[18:19]
	ds_read2_b32 v[80:81], v251 offset0:16 offset1:17
	v_max3_f32 v101, v101, v86, v87
	v_pk_mul_f32 v[34:35], v[34:35], v[234:235] op_sel_hi:[1,0]
	v_pk_mul_f32 v[32:33], v[32:33], v[234:235] op_sel_hi:[1,0]
	v_pk_mul_f32 v[62:63], v[62:63], v[234:235] op_sel_hi:[1,0]
	s_waitcnt lgkmcnt(0)
	v_fmamk_f32 v80, v88, 0x3e38aa3b, v80
	v_fmac_f32_e32 v81, 0x3e38aa3b, v89
	v_cndmask_b32_e64 v88, v243, v80, s[16:17]
	v_cndmask_b32_e64 v89, v243, v81, s[20:21]
	ds_read2_b32 v[80:81], v251 offset0:18 offset1:19
	v_max3_f32 v101, v101, v88, v89
	v_pk_mul_f32 v[60:61], v[60:61], v[234:235] op_sel_hi:[1,0]
	v_pk_mul_f32 v[58:59], v[58:59], v[234:235] op_sel_hi:[1,0]
	v_pk_mul_f32 v[56:57], v[56:57], v[234:235] op_sel_hi:[1,0]
	s_waitcnt lgkmcnt(0)
	v_fmamk_f32 v80, v90, 0x3e38aa3b, v80
	v_fmac_f32_e32 v81, 0x3e38aa3b, v91
	v_cndmask_b32_e64 v90, v243, v80, s[22:23]
	v_cndmask_b32_e64 v91, v243, v81, s[24:25]
	ds_read2_b32 v[80:81], v251 offset0:24 offset1:25
	v_max3_f32 v101, v101, v90, v91
	v_pk_mul_f32 v[54:55], v[54:55], v[234:235] op_sel_hi:[1,0]
	v_pk_mul_f32 v[52:53], v[52:53], v[234:235] op_sel_hi:[1,0]
	v_pk_mul_f32 v[50:51], v[50:51], v[234:235] op_sel_hi:[1,0]
	s_waitcnt lgkmcnt(0)
	v_fmamk_f32 v80, v92, 0x3e38aa3b, v80
	v_fmac_f32_e32 v81, 0x3e38aa3b, v93
	v_cndmask_b32_e64 v92, v243, v80, s[26:27]
	v_cndmask_b32_e64 v93, v243, v81, s[28:29]
	ds_read2_b32 v[80:81], v251 offset0:26 offset1:27
	v_max3_f32 v101, v101, v92, v93
	v_pk_mul_f32 v[48:49], v[48:49], v[234:235] op_sel_hi:[1,0]
	s_mul_i32 s4, s72, 0x2200
	s_movk_i32 s3, 0x420
	s_waitcnt lgkmcnt(0)
	v_fmamk_f32 v80, v94, 0x3e38aa3b, v80
	v_fmac_f32_e32 v81, 0x3e38aa3b, v95
	v_cndmask_b32_e64 v80, v243, v80, s[30:31]
	v_cndmask_b32_e64 v81, v243, v81, s[34:35]
	v_max3_f32 v94, v101, v80, v81
	v_cndmask_b32_e64 v95, v243, v64, s[36:37]
	v_cndmask_b32_e64 v101, v243, v177, s[38:39]
	v_max3_f32 v64, v94, v95, v101
	v_cndmask_b32_e64 v94, v243, v65, s[40:41]
	v_fmamk_f32 v65, v68, 0x3e38aa3b, v114
	v_max3_f32 v64, v64, v94, v67
	v_cndmask_b32_e64 v68, v243, v65, s[44:45]
	v_fmamk_f32 v65, v70, 0x3e38aa3b, v182
	v_max3_f32 v64, v64, v68, v69
	v_cndmask_b32_e64 v70, v243, v65, s[48:49]
	v_fmamk_f32 v65, v72, 0x3e38aa3b, v210
	v_max3_f32 v64, v64, v70, v71
	v_cndmask_b32_e64 v72, v243, v65, s[52:53]
	v_fmamk_f32 v65, v74, 0x3e38aa3b, v212
	v_max3_f32 v64, v64, v72, v73
	v_cndmask_b32_e64 v74, v243, v65, s[56:57]
	v_fmamk_f32 v65, v76, 0x3e38aa3b, v214
	v_max3_f32 v64, v64, v74, v75
	v_cndmask_b32_e64 v76, v243, v65, s[60:61]
	v_fmamk_f32 v65, v78, 0x3e38aa3b, v216
	v_max3_f32 v64, v64, v76, v77
	v_cndmask_b32_e64 v78, v243, v65, s[64:65]
	v_max3_f32 v64, v64, v78, v79
	ds_bpermute_b32 v65, v173, v64
	s_waitcnt lgkmcnt(0)
	v_max3_f32 v66, v179, v64, v65
	v_sub_f32_e32 v64, v97, v66
	v_exp_f32_e32 v219, v64
	v_sub_f32_e32 v97, v99, v66
	v_exp_f32_e32 v221, v97
	v_sub_f32_e32 v82, v82, v66
	v_exp_f32_e32 v223, v82
	v_sub_f32_e32 v82, v83, v66
	v_exp_f32_e32 v225, v82
	v_sub_f32_e32 v82, v84, v66
	v_pk_add_f32 v[64:65], v[218:219], 0 op_sel_hi:[1,0]
	v_exp_f32_e32 v227, v82
	v_sub_f32_e32 v82, v85, v66
	v_exp_f32_e32 v229, v82
	v_sub_f32_e32 v82, v86, v66
	v_pk_add_f32 v[64:65], v[220:221], v[64:65]
	v_exp_f32_e32 v231, v82
	v_sub_f32_e32 v82, v87, v66
	v_pk_add_f32 v[64:65], v[222:223], v[64:65]
	v_exp_f32_e32 v233, v82
	v_sub_f32_e32 v82, v88, v66
	v_pk_add_f32 v[64:65], v[224:225], v[64:65]
	v_exp_f32_e32 v185, v82
	v_sub_f32_e32 v82, v89, v66
	v_pk_add_f32 v[64:65], v[226:227], v[64:65]
	v_exp_f32_e32 v187, v82
	v_sub_f32_e32 v82, v90, v66
	v_pk_add_f32 v[64:65], v[228:229], v[64:65]
	v_exp_f32_e32 v189, v82
	v_sub_f32_e32 v82, v91, v66
	v_pk_add_f32 v[64:65], v[230:231], v[64:65]
	v_exp_f32_e32 v191, v82
	v_pk_add_f32 v[64:65], v[232:233], v[64:65]
	v_sub_f32_e32 v82, v92, v66
	v_pk_add_f32 v[64:65], v[184:185], v[64:65]
	v_exp_f32_e32 v193, v82
	v_sub_f32_e32 v82, v93, v66
	v_pk_add_f32 v[64:65], v[186:187], v[64:65]
	v_exp_f32_e32 v195, v82
	v_sub_f32_e32 v80, v80, v66
	v_pk_add_f32 v[64:65], v[188:189], v[64:65]
	v_exp_f32_e32 v207, v80
	v_sub_f32_e32 v80, v81, v66
	v_pk_add_f32 v[64:65], v[190:191], v[64:65]
	v_exp_f32_e32 v209, v80
	v_sub_f32_e32 v80, v95, v66
	v_exp_f32_e32 v117, v80
	v_sub_f32_e32 v80, v101, v66
	v_pk_add_f32 v[64:65], v[192:193], v[64:65]
	v_exp_f32_e32 v119, v80
	v_sub_f32_e32 v80, v94, v66
	v_pk_add_f32 v[64:65], v[194:195], v[64:65]
; #define LAS __attribute__((address_space(3)))
; __device__ __forceinline__ unsigned pk2c(float lo, float hi) { f32x2_t v = {lo, hi}; bf16x2_t b = __builtin_convertvector(v, bf16x2_t); return __builtin_bit_cast(unsigned, b); }
; __device__ __forceinline__ float shx(float v, int lane, int o) { return __builtin_bit_cast(float, __builtin_amdgcn_ds_bpermute((lane ^ o) << 2, __builtin_bit_cast(int, v))); }
; #define MFMA32(a, b, c) __builtin_amdgcn_mfma_f32_32x32x16_bf16((a), (b), (c), 0, 0, 0)
; template <int DQ, bool BIAS>
; __device__ __forceinline__ void attn_item_l0(const AttnItem& A, LAS unsigned char* lds, int wave_s_) {
;     ...
;                 mx = fmaxf(mx, shx(mx, lane, 32));
;                 const float mnew = fmaxf(mrun[qb], mx), alpha = __builtin_amdgcn_exp2f(mrun[qb] - mnew);
;                 mrun[qb] = mnew;
;                 float ls = 0.f;
; #pragma unroll
;                 for (int kbk = 0; kbk < 2; ++kbk)
; #pragma unroll
;                     for (int i = 0; i < 16; ++i) { const float p = __builtin_amdgcn_exp2f(s[kbk][qb][i] - mnew); s[kbk][qb][i] = p; ls += p; }
;                 lrun[qb] = lrun[qb] * alpha + ls;
; #pragma unroll
;                 for (int d = 0; d < 2; ++d)
; #pragma unroll
;                     for (int i = 0; i < 16; ++i) o[d][qb][i] *= alpha;
;             }
; #pragma unroll
;             for (int kbk = 0; kbk < 2; ++kbk)
; #pragma unroll
;                 for (int st = 0; st < 2; ++st) {
;                     bf16x8 pf[2];
; #pragma unroll
;                     for (int qb = 0; qb < 2; ++qb) { u32x4 pw;
; #pragma unroll
;                         for (int j = 0; j < 4; ++j) pw[j] = pk2c(s[kbk][qb][8 * st + 2 * j], s[kbk][qb][8 * st + 2 * j + 1]);
;                         pf[qb] = __builtin_bit_cast(bf16x8, pw); }
; #pragma unroll
;                     for (int d = 0; d < 2; ++d) {
;                         const LAS unsigned char* vp = vb + ((32 * d + r32) * OVSTR + 32 * kbk + 16 * st + 4 * hi) * 2;
;                         const s16x4 lo4 = *(const LAS s16x4*)vp, hi4 = *(const LAS s16x4*)(vp + 16);
;                         const bf16x8 vf = __builtin_shufflevector(lo4, hi4, 0, 1, 2, 3, 4, 5, 6, 7);
;                         o[d][0] = MFMA32(vf, pf[0], o[d][0]);
;                         o[d][1] = MFMA32(vf, pf[1], o[d][1]);
;                     }
;                 }
	v_exp_f32_e32 v121, v80
	v_sub_f32_e32 v67, v67, v66
	v_pk_add_f32 v[64:65], v[206:207], v[64:65]
	v_exp_f32_e32 v123, v67
	v_sub_f32_e32 v67, v68, v66
	v_pk_add_f32 v[64:65], v[208:209], v[64:65]
	v_exp_f32_e32 v125, v67
	v_sub_f32_e32 v67, v69, v66
	v_pk_add_f32 v[64:65], v[116:117], v[64:65]
	v_exp_f32_e32 v127, v67
	v_sub_f32_e32 v67, v70, v66
	v_pk_add_f32 v[64:65], v[118:119], v[64:65]
	v_sub_f32_e32 v112, v179, v66
	v_exp_f32_e32 v179, v67
	v_pk_add_f32 v[64:65], v[120:121], v[64:65]
	v_sub_f32_e32 v67, v71, v66
	v_pk_add_f32 v[64:65], v[122:123], v[64:65]
	v_exp_f32_e32 v181, v67
	v_sub_f32_e32 v67, v72, v66
	v_pk_add_f32 v[64:65], v[124:125], v[64:65]
	v_exp_f32_e32 v97, v67
	v_sub_f32_e32 v67, v73, v66
	v_pk_add_f32 v[64:65], v[126:127], v[64:65]
	v_exp_f32_e32 v99, v67
	v_sub_f32_e32 v67, v74, v66
	v_pk_add_f32 v[64:65], v[178:179], v[64:65]
	v_exp_f32_e32 v101, v67
	v_sub_f32_e32 v67, v75, v66
	v_exp_f32_e32 v103, v67
	v_sub_f32_e32 v67, v76, v66
	v_pk_add_f32 v[64:65], v[180:181], v[64:65]
	v_exp_f32_e32 v105, v67
	v_sub_f32_e32 v67, v77, v66
	v_pk_add_f32 v[64:65], v[96:97], v[64:65]
	v_exp_f32_e32 v107, v67
	v_sub_f32_e32 v67, v78, v66
	v_pk_add_f32 v[64:65], v[98:99], v[64:65]
	v_exp_f32_e32 v109, v67
	v_sub_f32_e32 v67, v79, v66
	v_pk_add_f32 v[64:65], v[100:101], v[64:65]
	v_exp_f32_e32 v111, v67
	v_pk_add_f32 v[64:65], v[102:103], v[64:65]
	v_exp_f32_e32 v235, v112
	v_pk_add_f32 v[64:65], v[104:105], v[64:65]
	v_cvt_pk_bf16_f32 v68, v218, v220
	v_pk_add_f32 v[64:65], v[106:107], v[64:65]
	v_cvt_pk_bf16_f32 v69, v222, v224
	v_pk_add_f32 v[64:65], v[108:109], v[64:65]
	v_cvt_pk_bf16_f32 v70, v226, v228
	v_pk_add_f32 v[64:65], v[110:111], v[64:65]
	v_cvt_pk_bf16_f32 v71, v230, v232
	v_pk_fma_f32 v[168:169], v[168:169], v[234:235], v[64:65]
	v_mov_b32_e32 v64, v235
	v_pk_mul_f32 v[30:31], v[30:31], v[64:65] op_sel_hi:[1,0]
	v_pk_mul_f32 v[28:29], v[28:29], v[64:65] op_sel_hi:[1,0]
	v_pk_mul_f32 v[26:27], v[26:27], v[64:65] op_sel_hi:[1,0]
	v_pk_mul_f32 v[24:25], v[24:25], v[64:65] op_sel_hi:[1,0]
	v_pk_mul_f32 v[22:23], v[22:23], v[64:65] op_sel_hi:[1,0]
	v_pk_mul_f32 v[20:21], v[20:21], v[64:65] op_sel_hi:[1,0]
	v_pk_mul_f32 v[18:19], v[18:19], v[64:65] op_sel_hi:[1,0]
	v_pk_mul_f32 v[16:17], v[16:17], v[64:65] op_sel_hi:[1,0]
	v_pk_mul_f32 v[14:15], v[14:15], v[64:65] op_sel_hi:[1,0]
	v_pk_mul_f32 v[12:13], v[12:13], v[64:65] op_sel_hi:[1,0]
	v_pk_mul_f32 v[10:11], v[10:11], v[64:65] op_sel_hi:[1,0]
	v_pk_mul_f32 v[8:9], v[8:9], v[64:65] op_sel_hi:[1,0]
	v_pk_mul_f32 v[6:7], v[6:7], v[64:65] op_sel_hi:[1,0]
	v_pk_mul_f32 v[4:5], v[4:5], v[64:65] op_sel_hi:[1,0]
	v_pk_mul_f32 v[2:3], v[2:3], v[64:65] op_sel_hi:[1,0]
	v_pk_mul_f32 v[0:1], v[0:1], v[64:65] op_sel_hi:[1,0]
	v_add3_u32 v65, v248, s4, v250
	v_add_u32_e32 v64, 0x6800, v65
	ds_read2_b64 v[76:79], v64 offset1:2
	ds_read2_b64 v[80:83], v64 offset0:4 offset1:6
	v_cvt_pk_bf16_f32 v72, v219, v221
	v_cvt_pk_bf16_f32 v73, v223, v225
	v_cvt_pk_bf16_f32 v74, v227, v229
	v_cvt_pk_bf16_f32 v75, v231, v233
	v_add_u32_e32 v65, 0x7800, v65
	s_waitcnt lgkmcnt(1)
	v_mfma_f32_32x32x16_bf16 v[32:47], v[76:79], v[68:71], v[32:47]
	v_mfma_f32_32x32x16_bf16 v[16:31], v[76:79], v[72:75], v[16:31]
	ds_read2_b64 v[76:79], v65 offset0:32 offset1:34
	s_waitcnt lgkmcnt(0)
	v_mfma_f32_32x32x16_bf16 v[48:63], v[76:79], v[68:71], v[48:63]
	v_cvt_pk_bf16_f32 v68, v184, v186
	v_cvt_pk_bf16_f32 v69, v188, v190
	v_cvt_pk_bf16_f32 v70, v192, v194
	v_cvt_pk_bf16_f32 v71, v206, v208
	v_mfma_f32_32x32x16_bf16 v[0:15], v[76:79], v[72:75], v[0:15]
	ds_read2_b64 v[76:79], v65 offset0:36 offset1:38
	v_cvt_pk_bf16_f32 v72, v185, v187
	v_cvt_pk_bf16_f32 v73, v189, v191
	v_cvt_pk_bf16_f32 v74, v193, v195
	v_cvt_pk_bf16_f32 v75, v207, v209
	s_waitcnt lgkmcnt(0)
	v_mfma_f32_32x32x16_bf16 v[48:63], v[76:79], v[68:71], v[48:63]
	v_mfma_f32_32x32x16_bf16 v[0:15], v[76:79], v[72:75], v[0:15]
	ds_read2_b64 v[76:79], v64 offset0:8 offset1:10
	v_mfma_f32_32x32x16_bf16 v[32:47], v[80:83], v[68:71], v[32:47]
	v_cvt_pk_bf16_f32 v68, v116, v118
	v_cvt_pk_bf16_f32 v69, v120, v122
	v_cvt_pk_bf16_f32 v70, v124, v126
	v_cvt_pk_bf16_f32 v71, v178, v180
	v_mov_b32_e32 v178, v196
	v_mfma_f32_32x32x16_bf16 v[16:31], v[80:83], v[72:75], v[16:31]
	v_cvt_pk_bf16_f32 v72, v117, v119
	v_cvt_pk_bf16_f32 v73, v121, v123
	v_cvt_pk_bf16_f32 v74, v125, v127
	v_cvt_pk_bf16_f32 v75, v179, v181
	v_mov_b32_e32 v179, v66
	s_waitcnt lgkmcnt(0)
	v_mfma_f32_32x32x16_bf16 v[32:47], v[76:79], v[68:71], v[32:47]
	v_mfma_f32_32x32x16_bf16 v[16:31], v[76:79], v[72:75], v[16:31]
	ds_read2_b64 v[76:79], v65 offset0:40 offset1:42
	s_waitcnt lgkmcnt(0)
	v_mfma_f32_32x32x16_bf16 v[48:63], v[76:79], v[68:71], v[48:63]
	v_cvt_pk_bf16_f32 v68, v96, v98
	v_cvt_pk_bf16_f32 v69, v100, v102
	v_cvt_pk_bf16_f32 v70, v104, v106
	v_cvt_pk_bf16_f32 v71, v108, v110
	v_mfma_f32_32x32x16_bf16 v[0:15], v[76:79], v[72:75], v[0:15]
	ds_read2_b64 v[76:79], v64 offset0:12 offset1:14
	v_cvt_pk_bf16_f32 v72, v97, v99
	v_cvt_pk_bf16_f32 v73, v101, v103
	v_cvt_pk_bf16_f32 v74, v105, v107
	v_cvt_pk_bf16_f32 v75, v109, v111
	s_waitcnt lgkmcnt(0)
	v_mfma_f32_32x32x16_bf16 v[32:47], v[76:79], v[68:71], v[32:47]
	v_mfma_f32_32x32x16_bf16 v[16:31], v[76:79], v[72:75], v[16:31]
	ds_read2_b64 v[76:79], v65 offset0:44 offset1:46
	s_waitcnt lgkmcnt(0)
	v_mfma_f32_32x32x16_bf16 v[48:63], v[76:79], v[68:71], v[48:63]
	v_mfma_f32_32x32x16_bf16 v[0:15], v[76:79], v[72:75], v[0:15]
